# speedup vs baseline: 1.0217x; 1.0027x over previous
.LBB0_86:
	s_mov_b32 s23, s10
	s_mov_b32 s10, s20
	s_add_i32 s24, s33, 2
	s_add_i32 s25, s10, 0
	v_add_u32_e32 v210, s25, v207
	v_mfma_f32_32x32x16_bf16 v[112:127], v[100:103], v[130:133], 0
	v_add_f32_e32 v100, v82, v80
	v_add_f32_e32 v101, v83, v81
	v_cvt_pk_bf16_f32 v158, v80, v81
	v_cvt_pk_bf16_f32 v159, v82, v83
	v_add_f32_e32 v80, v84, v100
	v_add_f32_e32 v81, v85, v101
	v_add_f32_e32 v146, v86, v80
	v_cvt_pk_bf16_f32 v160, v84, v85
	v_mfma_f32_32x32x16_bf16 v[96:111], v[96:99], v[130:133], 0
	v_add_f32_e32 v84, v87, v81
	v_cvt_pk_bf16_f32 v161, v86, v87
	ds_read_b64_tr_b16 v[80:81], v210 offset:49152
	ds_read_b64_tr_b16 v[82:83], v210 offset:49664
	v_add_f32_e32 v85, v88, v146
	v_add_f32_e32 v84, v89, v84
	v_mfma_f32_32x32x16_bf16 v[112:127], v[182:185], v[134:137], v[112:127]
	v_add_f32_e32 v146, v90, v85
	v_add_f32_e32 v147, v91, v84
	v_cvt_pk_bf16_f32 v154, v88, v89
	v_cvt_pk_bf16_f32 v155, v90, v91
	ds_read_b64_tr_b16 v[84:85], v210 offset:53248
	ds_read_b64_tr_b16 v[86:87], v210 offset:53760
	v_add_f32_e32 v88, v92, v146
	v_add_f32_e32 v89, v93, v147
	v_mfma_f32_32x32x16_bf16 v[96:111], v[178:181], v[134:137], v[96:111]
	v_add_f32_e32 v146, v94, v88
	v_add_f32_e32 v147, v95, v89
	v_cvt_pk_bf16_f32 v156, v92, v93
	v_cvt_pk_bf16_f32 v157, v94, v95
	ds_read_b64_tr_b16 v[88:89], v210 offset:57344
	ds_read_b64_tr_b16 v[90:91], v210 offset:57856
	v_add_f32_e32 v92, v64, v146
	v_add_f32_e32 v93, v65, v147
	v_mfma_f32_32x32x16_bf16 v[112:127], v[174:177], v[138:141], v[112:127]
	v_add_f32_e32 v92, v66, v92
	v_add_f32_e32 v93, v67, v93
	v_cvt_pk_bf16_f32 v150, v64, v65
	v_cvt_pk_bf16_f32 v151, v66, v67
	ds_read_b64_tr_b16 v[64:65], v210 offset:61440
	ds_read_b64_tr_b16 v[66:67], v210 offset:61952
	v_add_f32_e32 v92, v68, v92
	v_add_f32_e32 v93, v69, v93
	v_mfma_f32_32x32x16_bf16 v[96:111], v[170:173], v[138:141], v[96:111]
	v_add_f32_e32 v92, v70, v92
	v_add_f32_e32 v93, v71, v93
	v_cvt_pk_bf16_f32 v152, v68, v69
	v_cvt_pk_bf16_f32 v153, v70, v71
	v_add_f32_e32 v68, v72, v92
	v_add_f32_e32 v69, v73, v93
	v_mfma_f32_32x32x16_bf16 v[112:127], v[166:169], v[142:145], v[112:127]
	v_add_f32_e32 v68, v74, v68
	v_add_f32_e32 v69, v75, v69
	v_cvt_pk_bf16_f32 v146, v72, v73
	v_cvt_pk_bf16_f32 v147, v74, v75
	v_add_f32_e32 v68, v76, v68
	v_add_f32_e32 v69, v77, v69
	v_mfma_f32_32x32x16_bf16 v[96:111], v[162:165], v[142:145], v[96:111]
	v_add_f32_e32 v68, v78, v68
	v_add_f32_e32 v69, v79, v69
	v_cvt_pk_bf16_f32 v148, v76, v77
	v_cvt_pk_bf16_f32 v149, v78, v79
	s_nop 0
	v_exp_f32_e32 v112, v112
	v_exp_f32_e32 v113, v113
	s_waitcnt lgkmcnt(4)
	v_mfma_f32_32x32x16_bf16 v[48:63], v[80:83], v[158:161], v[48:63]
	v_add_f32_e32 v92, v68, v69
	ds_read_b64_tr_b16 v[68:69], v210 offset:50176
	ds_read_b64_tr_b16 v[70:71], v210 offset:50688
	v_exp_f32_e32 v114, v114
	v_exp_f32_e32 v115, v115
	v_mfma_f32_32x32x16_bf16 v[32:47], v[84:87], v[158:161], v[32:47]
	ds_read_b64_tr_b16 v[72:73], v210 offset:54272
	ds_read_b64_tr_b16 v[74:75], v210 offset:54784
	v_exp_f32_e32 v116, v116
	v_exp_f32_e32 v117, v117
	s_waitcnt lgkmcnt(4)
	v_mfma_f32_32x32x16_bf16 v[16:31], v[88:91], v[158:161], v[16:31]
	s_add_i32 s90, s33, 4
	s_min_u32 s90, s90, s19
	s_mul_i32 s90, s90, 0x160000
	s_add_i32 m0, s23, s5
	s_add_u32 s100, s44, s90
	s_addc_u32 s101, s45, 0
	global_load_lds_dwordx4 v199, s[100:101]
	ds_read_b64_tr_b16 v[76:77], v210 offset:58368
	ds_read_b64_tr_b16 v[78:79], v210 offset:58880
	v_exp_f32_e32 v118, v118
	v_exp_f32_e32 v119, v119
	v_mfma_f32_32x32x16_bf16 v[0:15], v[64:67], v[158:161], v[0:15]
	ds_read_b64_tr_b16 v[80:81], v210 offset:62464
	ds_read_b64_tr_b16 v[82:83], v210 offset:62976
	v_exp_f32_e32 v120, v120
	v_exp_f32_e32 v121, v121
	s_waitcnt lgkmcnt(4)
	v_mfma_f32_32x32x16_bf16 v[48:63], v[68:71], v[154:157], v[48:63]
	v_add_u32_e32 v64, s11, v204
	ds_read_b64_tr_b16 v[84:85], v210 offset:51200
	ds_read_b64_tr_b16 v[86:87], v210 offset:51712
	ds_read_b128 v[68:71], v64
	v_exp_f32_e32 v122, v122
	v_exp_f32_e32 v123, v123
	v_mfma_f32_32x32x16_bf16 v[32:47], v[72:75], v[154:157], v[32:47]
	ds_read_b64_tr_b16 v[72:73], v210 offset:55296
	ds_read_b64_tr_b16 v[74:75], v210 offset:55808
	ds_read_b128 v[64:67], v64 offset:4096
	v_exp_f32_e32 v124, v124
	v_exp_f32_e32 v125, v125
	s_waitcnt lgkmcnt(6)
	v_mfma_f32_32x32x16_bf16 v[16:31], v[76:79], v[154:157], v[16:31]
	s_add_i32 m0, s23, s32
	s_nop 0
	global_load_lds_dwordx4 v199, s[100:101] offset:128
	v_add_u32_e32 v88, s11, v128
	ds_read_b64_tr_b16 v[76:77], v210 offset:59392
	ds_read_b64_tr_b16 v[78:79], v210 offset:59904
	ds_read_b128 v[182:185], v88
	v_exp_f32_e32 v126, v126
	v_exp_f32_e32 v127, v127
	v_mfma_f32_32x32x16_bf16 v[0:15], v[80:83], v[154:157], v[0:15]
	ds_read_b64_tr_b16 v[80:81], v210 offset:63488
	ds_read_b64_tr_b16 v[82:83], v210 offset:64000
	ds_read_b128 v[178:181], v88 offset:4096
	v_exp_f32_e32 v96, v96
	v_exp_f32_e32 v97, v97
	s_waitcnt lgkmcnt(7)
	v_mfma_f32_32x32x16_bf16 v[48:63], v[84:87], v[150:153], v[48:63]
	v_add_u32_e32 v88, s11, v205
	ds_read_b64_tr_b16 v[84:85], v210 offset:52224
	ds_read_b64_tr_b16 v[86:87], v210 offset:52736
	ds_read_b128 v[174:177], v88
	v_exp_f32_e32 v98, v98
	v_exp_f32_e32 v99, v99
	v_mfma_f32_32x32x16_bf16 v[32:47], v[72:75], v[150:153], v[32:47]
	ds_read_b64_tr_b16 v[72:73], v210 offset:56320
	ds_read_b64_tr_b16 v[74:75], v210 offset:56832
	ds_read_b128 v[170:173], v88 offset:4096
	v_exp_f32_e32 v100, v100
	v_exp_f32_e32 v101, v101
	s_waitcnt lgkmcnt(7)
	v_mfma_f32_32x32x16_bf16 v[16:31], v[76:79], v[150:153], v[16:31]
	s_min_u32 s90, s24, s19
	s_mul_i32 s90, s90, 0x160000
	s_add_i32 m0, s11, s22
	s_add_u32 s100, s44, s90
	s_addc_u32 s101, s45, 0
	global_load_lds_dwordx4 v201, s[100:101]
	v_add_u32_e32 v88, s11, v206
	ds_read_b64_tr_b16 v[76:77], v210 offset:60416
	ds_read_b64_tr_b16 v[78:79], v210 offset:60928
	ds_read_b128 v[166:169], v88
	v_exp_f32_e32 v102, v102
	v_exp_f32_e32 v103, v103
	v_mfma_f32_32x32x16_bf16 v[0:15], v[80:83], v[150:153], v[0:15]
	ds_read_b64_tr_b16 v[80:81], v210 offset:64512
	ds_read_b64_tr_b16 v[82:83], v210 offset:65024
	ds_read_b128 v[162:165], v88 offset:4096
	v_exp_f32_e32 v104, v104
	v_exp_f32_e32 v105, v105
	s_waitcnt lgkmcnt(7)
	v_mfma_f32_32x32x16_bf16 v[48:63], v[84:87], v[146:149], v[48:63]
	v_exp_f32_e32 v106, v106
	v_exp_f32_e32 v107, v107
	v_mfma_f32_32x32x16_bf16 v[32:47], v[72:75], v[146:149], v[32:47]
	v_exp_f32_e32 v108, v108
	v_exp_f32_e32 v109, v109
	s_waitcnt lgkmcnt(1)
	v_mfma_f32_32x32x16_bf16 v[16:31], v[76:79], v[146:149], v[16:31]
	s_add_i32 m0, s11, s22
	s_addk_i32 m0, 0x400
	s_add_u32 s100, s100, 0x58000
	s_addc_u32 s101, s101, 0
	global_load_lds_dwordx4 v201, s[100:101]
	v_exp_f32_e32 v110, v110
	v_exp_f32_e32 v111, v111
	v_mfma_f32_32x32x16_bf16 v[0:15], v[80:83], v[146:149], v[0:15]
	s_waitcnt vmcnt(4) lgkmcnt(0)
	s_barrier
	v_add_f32_e32 v186, v209, v92
	v_add_u32_e32 v210, s23, v208
	v_mfma_f32_32x32x16_bf16 v[80:95], v[68:71], v[130:133], 0
	v_add_f32_e32 v68, v114, v112
	v_add_f32_e32 v69, v115, v113
	v_cvt_pk_bf16_f32 v158, v112, v113
	v_cvt_pk_bf16_f32 v159, v114, v115
	v_add_f32_e32 v68, v116, v68
	v_add_f32_e32 v112, v117, v69
	v_add_f32_e32 v146, v118, v68
	v_cvt_pk_bf16_f32 v160, v116, v117
	v_mfma_f32_32x32x16_bf16 v[64:79], v[64:67], v[130:133], 0
	v_add_f32_e32 v116, v119, v112
	v_cvt_pk_bf16_f32 v161, v118, v119
	ds_read_b64_tr_b16 v[112:113], v210 offset:49152
	ds_read_b64_tr_b16 v[114:115], v210 offset:49664
	v_add_f32_e32 v117, v120, v146
	v_add_f32_e32 v116, v121, v116
	v_mfma_f32_32x32x16_bf16 v[80:95], v[182:185], v[134:137], v[80:95]
	v_add_f32_e32 v146, v122, v117
	v_add_f32_e32 v147, v123, v116
	v_cvt_pk_bf16_f32 v154, v120, v121
	v_cvt_pk_bf16_f32 v155, v122, v123
	ds_read_b64_tr_b16 v[116:117], v210 offset:53248
	ds_read_b64_tr_b16 v[118:119], v210 offset:53760
	v_add_f32_e32 v120, v124, v146
	v_add_f32_e32 v121, v125, v147
	v_mfma_f32_32x32x16_bf16 v[64:79], v[178:181], v[134:137], v[64:79]
	v_add_f32_e32 v146, v126, v120
	v_add_f32_e32 v147, v127, v121
	v_cvt_pk_bf16_f32 v156, v124, v125
	v_cvt_pk_bf16_f32 v157, v126, v127
	ds_read_b64_tr_b16 v[120:121], v210 offset:57344
	ds_read_b64_tr_b16 v[122:123], v210 offset:57856
	v_add_f32_e32 v124, v96, v146
	v_add_f32_e32 v125, v97, v147
	v_mfma_f32_32x32x16_bf16 v[80:95], v[174:177], v[138:141], v[80:95]
	v_add_f32_e32 v124, v98, v124
	v_add_f32_e32 v125, v99, v125
	v_cvt_pk_bf16_f32 v150, v96, v97
	v_cvt_pk_bf16_f32 v151, v98, v99
	ds_read_b64_tr_b16 v[96:97], v210 offset:61440
	ds_read_b64_tr_b16 v[98:99], v210 offset:61952
	v_add_f32_e32 v124, v100, v124
	v_add_f32_e32 v125, v101, v125
	v_mfma_f32_32x32x16_bf16 v[64:79], v[170:173], v[138:141], v[64:79]
	v_add_f32_e32 v124, v102, v124
	v_add_f32_e32 v125, v103, v125
	v_cvt_pk_bf16_f32 v152, v100, v101
	v_cvt_pk_bf16_f32 v153, v102, v103
	v_add_f32_e32 v100, v104, v124
	v_add_f32_e32 v101, v105, v125
	v_mfma_f32_32x32x16_bf16 v[80:95], v[166:169], v[142:145], v[80:95]
	v_add_f32_e32 v100, v106, v100
	v_add_f32_e32 v101, v107, v101
	v_cvt_pk_bf16_f32 v146, v104, v105
	v_cvt_pk_bf16_f32 v147, v106, v107
	v_add_f32_e32 v100, v108, v100
	v_add_f32_e32 v101, v109, v101
	v_mfma_f32_32x32x16_bf16 v[64:79], v[162:165], v[142:145], v[64:79]
	v_add_f32_e32 v100, v110, v100
	v_add_f32_e32 v101, v111, v101
	v_cvt_pk_bf16_f32 v148, v108, v109
	v_cvt_pk_bf16_f32 v149, v110, v111
	v_add_f32_e32 v100, v100, v101
	v_exp_f32_e32 v80, v80
	v_exp_f32_e32 v81, v81
	s_waitcnt lgkmcnt(4)
	v_mfma_f32_32x32x16_bf16 v[48:63], v[112:115], v[158:161], v[48:63]
	v_add_f32_e32 v209, v186, v100
	ds_read_b64_tr_b16 v[100:101], v210 offset:50176
	ds_read_b64_tr_b16 v[102:103], v210 offset:50688
	v_exp_f32_e32 v82, v82
	v_exp_f32_e32 v83, v83
	v_mfma_f32_32x32x16_bf16 v[32:47], v[116:119], v[158:161], v[32:47]
	ds_read_b64_tr_b16 v[104:105], v210 offset:54272
	ds_read_b64_tr_b16 v[106:107], v210 offset:54784
	v_exp_f32_e32 v84, v84
	v_exp_f32_e32 v85, v85
	s_waitcnt lgkmcnt(4)
	v_mfma_f32_32x32x16_bf16 v[16:31], v[120:123], v[158:161], v[16:31]
	s_add_i32 s90, s33, 5
	s_min_u32 s90, s90, s19
	s_mul_i32 s90, s90, 0x160000
	s_add_i32 m0, s11, s5
	s_add_u32 s100, s44, s90
	s_addc_u32 s101, s45, 0
	global_load_lds_dwordx4 v199, s[100:101]
	ds_read_b64_tr_b16 v[108:109], v210 offset:58368
	ds_read_b64_tr_b16 v[110:111], v210 offset:58880
	v_exp_f32_e32 v86, v86
	v_exp_f32_e32 v87, v87
	v_mfma_f32_32x32x16_bf16 v[0:15], v[96:99], v[158:161], v[0:15]
	ds_read_b64_tr_b16 v[112:113], v210 offset:62464
	ds_read_b64_tr_b16 v[114:115], v210 offset:62976
	v_exp_f32_e32 v88, v88
	v_exp_f32_e32 v89, v89
	s_waitcnt lgkmcnt(4)
	v_mfma_f32_32x32x16_bf16 v[48:63], v[100:103], v[154:157], v[48:63]
	v_add_u32_e32 v96, s25, v204
	ds_read_b64_tr_b16 v[116:117], v210 offset:51200
	ds_read_b64_tr_b16 v[118:119], v210 offset:51712
	ds_read_b128 v[100:103], v96
	v_exp_f32_e32 v90, v90
	v_exp_f32_e32 v91, v91
	v_mfma_f32_32x32x16_bf16 v[32:47], v[104:107], v[154:157], v[32:47]
	ds_read_b64_tr_b16 v[104:105], v210 offset:55296
	ds_read_b64_tr_b16 v[106:107], v210 offset:55808
	ds_read_b128 v[96:99], v96 offset:4096
	v_exp_f32_e32 v92, v92
	v_exp_f32_e32 v93, v93
	s_waitcnt lgkmcnt(6)
	v_mfma_f32_32x32x16_bf16 v[16:31], v[108:111], v[154:157], v[16:31]
	s_add_i32 m0, s11, s32
	s_nop 0
	global_load_lds_dwordx4 v199, s[100:101] offset:128
	v_add_u32_e32 v120, s25, v128
	ds_read_b64_tr_b16 v[108:109], v210 offset:59392
	ds_read_b64_tr_b16 v[110:111], v210 offset:59904
	ds_read_b128 v[182:185], v120
	v_exp_f32_e32 v94, v94
	v_exp_f32_e32 v95, v95
	v_mfma_f32_32x32x16_bf16 v[0:15], v[112:115], v[154:157], v[0:15]
	ds_read_b64_tr_b16 v[112:113], v210 offset:63488
	ds_read_b64_tr_b16 v[114:115], v210 offset:64000
	ds_read_b128 v[178:181], v120 offset:4096
	v_exp_f32_e32 v64, v64
	v_exp_f32_e32 v65, v65
	s_waitcnt lgkmcnt(7)
	v_mfma_f32_32x32x16_bf16 v[48:63], v[116:119], v[150:153], v[48:63]
	v_add_u32_e32 v120, s25, v205
	ds_read_b64_tr_b16 v[116:117], v210 offset:52224
	ds_read_b64_tr_b16 v[118:119], v210 offset:52736
	ds_read_b128 v[174:177], v120
	v_exp_f32_e32 v66, v66
	v_exp_f32_e32 v67, v67
	v_mfma_f32_32x32x16_bf16 v[32:47], v[104:107], v[150:153], v[32:47]
	ds_read_b64_tr_b16 v[104:105], v210 offset:56320
	ds_read_b64_tr_b16 v[106:107], v210 offset:56832
	ds_read_b128 v[170:173], v120 offset:4096
	v_exp_f32_e32 v68, v68
	v_exp_f32_e32 v69, v69
	s_waitcnt lgkmcnt(7)
	v_mfma_f32_32x32x16_bf16 v[16:31], v[108:111], v[150:153], v[16:31]
	s_add_i32 s90, s33, 3
	s_min_u32 s90, s90, s19
	s_mul_i32 s90, s90, 0x160000
	s_add_i32 m0, s10, s22
	s_add_u32 s100, s44, s90
	s_addc_u32 s101, s45, 0
	global_load_lds_dwordx4 v201, s[100:101]
	v_add_u32_e32 v120, s25, v206
	ds_read_b64_tr_b16 v[108:109], v210 offset:60416
	ds_read_b64_tr_b16 v[110:111], v210 offset:60928
	ds_read_b128 v[166:169], v120
	v_exp_f32_e32 v70, v70
	v_exp_f32_e32 v71, v71
	v_mfma_f32_32x32x16_bf16 v[0:15], v[112:115], v[150:153], v[0:15]
	ds_read_b64_tr_b16 v[112:113], v210 offset:64512
	ds_read_b64_tr_b16 v[114:115], v210 offset:65024
	ds_read_b128 v[162:165], v120 offset:4096
	v_exp_f32_e32 v72, v72
	v_exp_f32_e32 v73, v73
	s_waitcnt lgkmcnt(7)
	v_mfma_f32_32x32x16_bf16 v[48:63], v[116:119], v[146:149], v[48:63]
	v_exp_f32_e32 v74, v74
	v_exp_f32_e32 v75, v75
	v_mfma_f32_32x32x16_bf16 v[32:47], v[104:107], v[146:149], v[32:47]
	v_exp_f32_e32 v76, v76
	v_exp_f32_e32 v77, v77
	s_waitcnt lgkmcnt(1)
	v_mfma_f32_32x32x16_bf16 v[16:31], v[108:111], v[146:149], v[16:31]
	s_add_i32 m0, s10, s22
	s_addk_i32 m0, 0x400
	s_add_u32 s100, s100, 0x58000
	s_addc_u32 s101, s101, 0
	global_load_lds_dwordx4 v201, s[100:101]
	v_exp_f32_e32 v78, v78
	v_exp_f32_e32 v79, v79
	v_mfma_f32_32x32x16_bf16 v[0:15], v[112:115], v[146:149], v[0:15]
	s_waitcnt vmcnt(4) lgkmcnt(0)
	s_barrier
	s_cmp_ge_u32 s24, s4
	s_mov_b32 s20, s11
	s_mov_b32 s11, s23
	s_mov_b32 s33, s24
	s_cbranch_scc0 .LBB0_86
	ds_bpermute_b32 v64, v246, v209
	s_waitcnt vmcnt(0)
	s_barrier
	s_cmpk_lt_u32 s17, 0x100
	s_mov_b64 s[10:11], -1
	s_waitcnt lgkmcnt(0)
	v_add_f32_e32 v64, v209, v64
	v_div_scale_f32 v65, s[4:5], v64, v64, 1.0
	v_rcp_f32_e32 v66, v65
	v_div_scale_f32 v67, vcc, 1.0, v64, 1.0
	s_cselect_b64 s[4:5], -1, 0
	v_fma_f32 v68, -v65, v66, 1.0
	v_fmac_f32_e32 v66, v68, v66
	v_mul_f32_e32 v68, v67, v66
	v_fma_f32 v69, -v65, v68, v67
	v_fmac_f32_e32 v68, v69, v66
	v_fma_f32 v65, -v65, v68, v67
	v_div_fmas_f32 v65, v65, v66, v68
	v_div_fixup_f32 v134, v65, v64, 1.0
	s_and_b64 vcc, exec, s[4:5]
	s_cbranch_vccnz .LBB0_89
	s_lshl_b32 s10, s18, 14
	s_add_i32 s10, s10, 0
	v_mul_f32_e32 v64, v48, v134
	v_lshl_add_u32 v65, v202, 2, s10
	v_mul_f32_e32 v66, v49, v134
	ds_write2st64_b32 v65, v64, v66 offset1:1
	v_mul_f32_e32 v64, v50, v134
	v_mul_f32_e32 v66, v51, v134
	ds_write2st64_b32 v65, v64, v66 offset0:2 offset1:3
	v_mul_f32_e32 v64, v52, v134
	v_mul_f32_e32 v66, v53, v134
	ds_write2st64_b32 v65, v64, v66 offset0:4 offset1:5
	v_mul_f32_e32 v64, v54, v134
	v_mul_f32_e32 v66, v55, v134
	ds_write2st64_b32 v65, v64, v66 offset0:6 offset1:7
	v_mul_f32_e32 v64, v56, v134
	v_mul_f32_e32 v66, v57, v134
	ds_write2st64_b32 v65, v64, v66 offset0:8 offset1:9
	v_mul_f32_e32 v64, v58, v134
	v_mul_f32_e32 v66, v59, v134
	ds_write2st64_b32 v65, v64, v66 offset0:10 offset1:11
	v_mul_f32_e32 v64, v60, v134
	v_mul_f32_e32 v66, v61, v134
	ds_write2st64_b32 v65, v64, v66 offset0:12 offset1:13
	v_mul_f32_e32 v64, v62, v134
	v_mul_f32_e32 v66, v63, v134
	ds_write2st64_b32 v65, v64, v66 offset0:14 offset1:15
	v_mul_f32_e32 v64, v32, v134
	v_mul_f32_e32 v66, v33, v134
	ds_write2st64_b32 v65, v64, v66 offset0:16 offset1:17
	v_mul_f32_e32 v64, v34, v134
	v_mul_f32_e32 v66, v35, v134
	ds_write2st64_b32 v65, v64, v66 offset0:18 offset1:19
	v_mul_f32_e32 v64, v36, v134
	v_mul_f32_e32 v66, v37, v134
	ds_write2st64_b32 v65, v64, v66 offset0:20 offset1:21
	v_mul_f32_e32 v64, v38, v134
	v_mul_f32_e32 v66, v39, v134
	ds_write2st64_b32 v65, v64, v66 offset0:22 offset1:23
	v_mul_f32_e32 v64, v40, v134
	v_mul_f32_e32 v66, v41, v134
	ds_write2st64_b32 v65, v64, v66 offset0:24 offset1:25
	v_mul_f32_e32 v64, v42, v134
	v_mul_f32_e32 v66, v43, v134
	ds_write2st64_b32 v65, v64, v66 offset0:26 offset1:27
	v_mul_f32_e32 v64, v44, v134
	v_mul_f32_e32 v66, v45, v134
	ds_write2st64_b32 v65, v64, v66 offset0:28 offset1:29
	v_mul_f32_e32 v64, v46, v134
	v_mul_f32_e32 v66, v47, v134
	ds_write2st64_b32 v65, v64, v66 offset0:30 offset1:31
	v_mul_f32_e32 v64, v16, v134
	v_mul_f32_e32 v66, v17, v134
	ds_write2st64_b32 v65, v64, v66 offset0:32 offset1:33
	v_mul_f32_e32 v64, v18, v134
	v_mul_f32_e32 v66, v19, v134
	ds_write2st64_b32 v65, v64, v66 offset0:34 offset1:35
	v_mul_f32_e32 v64, v20, v134
	v_mul_f32_e32 v66, v21, v134
	ds_write2st64_b32 v65, v64, v66 offset0:36 offset1:37
	v_mul_f32_e32 v64, v22, v134
	v_mul_f32_e32 v66, v23, v134
	ds_write2st64_b32 v65, v64, v66 offset0:38 offset1:39
	v_mul_f32_e32 v64, v24, v134
	v_mul_f32_e32 v66, v25, v134
	ds_write2st64_b32 v65, v64, v66 offset0:40 offset1:41
	v_mul_f32_e32 v64, v26, v134
	v_mul_f32_e32 v66, v27, v134
	ds_write2st64_b32 v65, v64, v66 offset0:42 offset1:43
	v_mul_f32_e32 v64, v28, v134
	v_mul_f32_e32 v66, v29, v134
	ds_write2st64_b32 v65, v64, v66 offset0:44 offset1:45
	v_mul_f32_e32 v64, v30, v134
	v_mul_f32_e32 v66, v31, v134
	ds_write2st64_b32 v65, v64, v66 offset0:46 offset1:47
	v_mul_f32_e32 v64, v0, v134
	v_mul_f32_e32 v66, v1, v134
	ds_write2st64_b32 v65, v64, v66 offset0:48 offset1:49
	v_mul_f32_e32 v64, v2, v134
	v_mul_f32_e32 v66, v3, v134
	ds_write2st64_b32 v65, v64, v66 offset0:50 offset1:51
	v_mul_f32_e32 v64, v4, v134
	v_mul_f32_e32 v66, v5, v134
	ds_write2st64_b32 v65, v64, v66 offset0:52 offset1:53
	v_mul_f32_e32 v64, v6, v134
	v_mul_f32_e32 v66, v7, v134
	ds_write2st64_b32 v65, v64, v66 offset0:54 offset1:55
	v_mul_f32_e32 v64, v8, v134
	v_mul_f32_e32 v66, v9, v134
	ds_write2st64_b32 v65, v64, v66 offset0:56 offset1:57
	v_mul_f32_e32 v64, v10, v134
	v_mul_f32_e32 v66, v11, v134
	ds_write2st64_b32 v65, v64, v66 offset0:58 offset1:59
	v_mul_f32_e32 v64, v12, v134
	v_mul_f32_e32 v66, v13, v134
	ds_write2st64_b32 v65, v64, v66 offset0:60 offset1:61
	v_mul_f32_e32 v64, v14, v134
	v_mul_f32_e32 v66, v15, v134
	s_mov_b64 s[10:11], 0
	ds_write2st64_b32 v65, v64, v66 offset0:62 offset1:63
